# phase F: first GEMM's prologue no longer drains the previous sub-tile's stores before its LDS-DMA loads (vmcnt(0) -> lgkmcnt(0))
# baseline (speedup 1.0000x reference)
; #define WAIT_V(n) asm volatile("s_waitcnt vmcnt(" #n ")" ::: "memory")
; #define BAR __builtin_amdgcn_s_barrier()
; DI void gemm256(int wv0, f32x4 (&acc)[2][2][4][2], const u16* __restrict__ A, int lda, const u16* __restrict__ Bt, int ldb,
;                 int K, unsigned char* smem) {
;   u16* shm = (u16*)smem;
;   const int tid = my_tid(wv0), lane = tid & 63;
;   const int wr = wv0 >> 2, wc = wv0 & 3, fr = lane & 15, fq = lane >> 4;
;     ...
;   int sr0, sc0, sr1, sc1;
;   stage_rc(tid * 16, sr0, sc0);
;   stage_rc(tid * 16 + 8192, sr1, sc1);
;   const u16* a0 = A + (size_t)sr0 * lda + sc0;
;   const u16* a1 = A + (size_t)sr1 * lda + sc1;
;   const u16* b0 = Bt + (size_t)sr0 * ldb + sc0;
;   const u16* b1 = Bt + (size_t)sr1 * ldb + sc1;
;     ...
;   WAIT_V(0);
;   __syncthreads();
;   STAGE_B(SB(0, 0), 0, 0) STAGE_A(SA(0, 0), 0, 0)
;   STAGE_B(SB(0, 1), 1, 0) STAGE_A(SA(0, 1), 1, 0)
;   if (wr == 1) BAR;
.LBB0_983:
	v_mov_b32_e32 v12, v148
	s_or_b32 s33, s10, s96
	v_bfe_i32 v1, v12, 27, 1
	v_lshlrev_b32_e32 v13, 4, v12
	v_lshrrev_b32_e32 v1, 22, v1
	v_add_u32_e32 v1, v13, v1
	v_and_b32_e32 v1, 0xfffffc00, v1
	v_ashrrev_i32_e32 v0, 31, v12
	v_sub_u32_e32 v1, v13, v1
	v_lshrrev_b32_e32 v0, 26, v0
	v_lshrrev_b32_e32 v2, 4, v1
	v_add_u32_e32 v0, v12, v0
	v_bitop3_b32 v2, v2, v1, 32 bitop3:0x6c
	v_ashrrev_i32_e32 v1, 31, v1
	v_ashrrev_i32_e32 v0, 6, v0
	v_lshrrev_b32_e32 v1, 26, v1
	v_lshlrev_b32_e32 v3, 3, v0
	v_add_u32_e32 v1, v2, v1
	v_and_b32_e32 v3, -16, v3
	v_ashrrev_i32_e32 v1, 6, v1
	v_add_u32_e32 v4, v1, v3
	v_mul_i32_i24_e32 v1, 64, v1
	v_lshlrev_b32_e32 v0, 5, v0
	v_sub_u32_e32 v1, v2, v1
	v_and_b32_e32 v0, 32, v0
	v_ashrrev_i16_sdwa v1, v150, sext(v1) dst_sel:DWORD dst_unused:UNUSED_PAD src0_sel:DWORD src1_sel:BYTE_0
	v_add_u32_sdwa v0, v0, sext(v1) dst_sel:DWORD dst_unused:UNUSED_PAD src0_sel:DWORD src1_sel:WORD_0
	v_add_u32_e32 v1, 0x2000, v13
	v_ashrrev_i32_e32 v2, 31, v1
	v_lshrrev_b32_e32 v2, 22, v2
	v_add_u32_e32 v2, v1, v2
	v_ashrrev_i32_e32 v2, 10, v2
	v_mul_i32_i24_e32 v3, 0x400, v2
	v_sub_u32_e32 v1, v1, v3
	v_lshrrev_b32_e32 v3, 4, v1
	v_bitop3_b32 v1, v3, v1, 32 bitop3:0x6c
	v_ashrrev_i32_e32 v5, 31, v1
	v_lshrrev_b32_e32 v5, 26, v5
	v_lshlrev_b32_e32 v3, 3, v2
	v_add_u32_e32 v5, v1, v5
	v_and_b32_e32 v3, -16, v3
	v_ashrrev_i32_e32 v6, 6, v5
	s_lshl_b32 s0, s33, 18
	v_add_u32_e32 v8, v6, v3
	v_and_b32_e32 v3, 0xc0, v5
	s_add_u32 s0, s75, s0
	v_lshlrev_b32_e32 v2, 5, v2
	v_sub_u32_e32 v1, v1, v3
	s_addc_u32 s1, s76, 0
	v_and_b32_e32 v2, 32, v2
	v_ashrrev_i16_sdwa v1, v150, sext(v1) dst_sel:DWORD dst_unused:UNUSED_PAD src0_sel:DWORD src1_sel:BYTE_0
	v_ashrrev_i32_e32 v5, 31, v4
	v_ashrrev_i32_e32 v9, 31, v8
	s_add_i32 s6, 32, 0x10000
	v_add_u32_sdwa v2, v2, sext(v1) dst_sel:DWORD dst_unused:UNUSED_PAD src0_sel:DWORD src1_sel:WORD_0
	v_ashrrev_i32_e32 v1, 31, v0
	v_lshlrev_b64 v[6:7], 10, v[4:5]
	v_lshlrev_b64 v[4:5], 10, v[8:9]
	v_add_u32_e32 v145, s6, v13
	v_ashrrev_i32_e32 v3, 31, v2
	v_lshl_add_u64 v[10:11], s[0:1], 0, v[6:7]
	v_lshl_add_u64 v[8:9], s[0:1], 0, v[4:5]
	v_lshlrev_b64 v[16:17], 1, v[0:1]
	v_readfirstlane_b32 s0, v145
	v_add_u32_e32 v146, 0x2000, v145
	v_lshlrev_b64 v[18:19], 1, v[2:3]
	v_lshl_add_u64 v[10:11], v[10:11], 0, v[16:17]
	s_mov_b32 m0, s0
	v_readfirstlane_b32 s0, v146
	v_add_u32_e32 v147, 32, v13
	v_lshl_add_u64 v[14:15], s[68:69], 0, v[6:7]
	v_lshl_add_u64 v[8:9], v[8:9], 0, v[18:19]
	s_waitcnt lgkmcnt(0)
	s_barrier
	global_load_lds_dwordx4 v[10:11], off
	s_mov_b32 m0, s0
	v_readfirstlane_b32 s0, v147
	v_add_u32_e32 v152, 0x2000, v147
	s_add_i32 s7, 32, 0x14000
	v_lshl_add_u64 v[132:133], v[14:15], 0, v[16:17]
	v_lshl_add_u64 v[14:15], s[68:69], 0, v[4:5]
	global_load_lds_dwordx4 v[8:9], off
	s_mov_b32 m0, s0
	v_readfirstlane_b32 s0, v152
	v_add_u32_e32 v153, s7, v13
	v_lshl_add_u64 v[130:131], v[14:15], 0, v[18:19]
	global_load_lds_dwordx4 v[132:133], off
	s_mov_b32 m0, s0
	v_readfirstlane_b32 s0, v153
	v_add_u32_e32 v154, 0x2000, v153
	global_load_lds_dwordx4 v[130:131], off
	v_lshl_add_u64 v[14:15], v[10:11], 0, s[22:23]
	s_mov_b32 m0, s0
	v_readfirstlane_b32 s0, v154
	v_add_u32_e32 v155, 0x4000, v147
	global_load_lds_dwordx4 v[14:15], off
	v_lshl_add_u64 v[14:15], v[8:9], 0, s[22:23]
	s_mov_b32 m0, s0
	v_readfirstlane_b32 s0, v155
	v_add_u32_e32 v156, 0x6000, v147
	global_load_lds_dwordx4 v[14:15], off
	v_lshl_add_u64 v[14:15], v[132:133], 0, s[22:23]
	s_mov_b32 m0, s0
	v_readfirstlane_b32 s0, v156
	global_load_lds_dwordx4 v[14:15], off
	v_lshl_add_u64 v[14:15], v[130:131], 0, s[22:23]
	s_mov_b32 m0, s0
	v_cmp_ne_u32_e64 s[2:3], 1, v149
	global_load_lds_dwordx4 v[14:15], off
	s_andn2_b64 vcc, exec, s[16:17]
	s_cbranch_vccnz .LBB0_985
	s_barrier
